# stack10 + GEMM unit heads clear the 128 accumulators with 64 v_mov_b64 instead of 127 v_mov_b32
# baseline (speedup 1.0000x reference)
; template <class Epi, class Sched, bool ALIGN_EPI = false, bool SP2 = false>
; __device__ __forceinline__ void gemm_phase(PG8_LAS unsigned char* lds, const Gemm g, const Sched& S, const Epi& E, int wid_in) {
;     ...
;         const char* nA = has_next ? (const char*)g.A + (size_t)nxt.pm * tstep + (size_t)nxt.kt0 * kstep : cA; const char* nB = has_next ? (const char*)g.Bt + (size_t)nxt.pn * tstep + (size_t)nxt.kt0 * kstep : cB;
;         const int nt = cur.nkt;
;     ...
; #pragma unroll
;         for (int a = 0; a < 2; ++a)
; #pragma unroll
;             for (int b = 0; b < 2; ++b)
; #pragma unroll
;                 for (int m = 0; m < 4; ++m)
; #pragma unroll
;                     for (int n = 0; n < 2; ++n) acc[a][b][m][n] = (f32x4){0.f, 0.f, 0.f, 0.f};
.LBB0_277:
	s_ashr_i32 s19, s18, 31
	s_lshl_b64 s[22:23], s[18:19], 20
	s_add_u32 s22, s0, s22
	s_addc_u32 s23, s1, s23
	s_and_b64 s[24:25], s[20:21], exec
	s_cselect_b32 s11, s23, s27
	s_cselect_b32 s19, s22, s26
	s_ashr_i32 s17, s16, 31
	s_lshl_b64 s[24:25], s[16:17], 20
	s_add_u32 s24, s34, s24
	s_addc_u32 s25, s35, s25
	s_and_b64 s[30:31], s[20:21], exec
	s_cselect_b32 s17, s25, s29
	s_cselect_b32 s62, s24, s28
	s_add_u32 s64, s28, 0x100
	s_addc_u32 s65, s29, 0
	s_add_u32 s26, s26, 0x80080
	v_mov_b32_e32 v2, 0
	s_addc_u32 s27, s27, 0
	s_mov_b32 s63, -2
	v_mov_b64_e32 v[2:3], 0
	v_mov_b64_e32 v[4:5], 0
	v_mov_b64_e32 v[6:7], 0
	v_mov_b64_e32 v[8:9], 0
	v_mov_b64_e32 v[10:11], 0
	v_mov_b64_e32 v[12:13], 0
	v_mov_b64_e32 v[14:15], 0
	v_mov_b64_e32 v[16:17], 0
	v_mov_b64_e32 v[18:19], 0
	v_mov_b64_e32 v[20:21], 0
	v_mov_b64_e32 v[22:23], 0
	v_mov_b64_e32 v[24:25], 0
	v_mov_b64_e32 v[26:27], 0
	v_mov_b64_e32 v[28:29], 0
	v_mov_b64_e32 v[30:31], 0
	v_mov_b64_e32 v[32:33], 0
	v_mov_b64_e32 v[34:35], 0
	v_mov_b64_e32 v[36:37], 0
	v_mov_b64_e32 v[38:39], 0
	v_mov_b64_e32 v[40:41], 0
	v_mov_b64_e32 v[42:43], 0
	v_mov_b64_e32 v[44:45], 0
	v_mov_b64_e32 v[46:47], 0
	v_mov_b64_e32 v[48:49], 0
	v_mov_b64_e32 v[50:51], 0
	v_mov_b64_e32 v[52:53], 0
	v_mov_b64_e32 v[54:55], 0
	v_mov_b64_e32 v[56:57], 0
	v_mov_b64_e32 v[58:59], 0
	v_mov_b64_e32 v[60:61], 0
	v_mov_b64_e32 v[62:63], 0
	v_mov_b64_e32 v[64:65], 0
	v_mov_b64_e32 v[66:67], 0
	v_mov_b64_e32 v[68:69], 0
	v_mov_b64_e32 v[70:71], 0
	v_mov_b64_e32 v[72:73], 0
	v_mov_b64_e32 v[74:75], 0
	v_mov_b64_e32 v[76:77], 0
	v_mov_b64_e32 v[78:79], 0
	v_mov_b64_e32 v[80:81], 0
	v_mov_b64_e32 v[82:83], 0
	v_mov_b64_e32 v[84:85], 0
	v_mov_b64_e32 v[86:87], 0
	v_mov_b64_e32 v[88:89], 0
	v_mov_b64_e32 v[90:91], 0
	v_mov_b64_e32 v[92:93], 0
	v_mov_b64_e32 v[94:95], 0
	v_mov_b64_e32 v[96:97], 0
	v_mov_b64_e32 v[98:99], 0
	v_mov_b64_e32 v[100:101], 0
	v_mov_b64_e32 v[102:103], 0
	v_mov_b64_e32 v[104:105], 0
	v_mov_b64_e32 v[106:107], 0
	v_mov_b64_e32 v[108:109], 0
	v_mov_b64_e32 v[110:111], 0
	v_mov_b64_e32 v[112:113], 0
	v_mov_b64_e32 v[114:115], 0
	v_mov_b64_e32 v[116:117], 0
	v_mov_b64_e32 v[118:119], 0
	v_mov_b64_e32 v[120:121], 0
	v_mov_b64_e32 v[122:123], 0
	v_mov_b64_e32 v[124:125], 0
	v_mov_b64_e32 v[126:127], 0
	v_mov_b64_e32 v[128:129], 0
	s_cmp_ge_u32 s47, 4
	s_cbranch_scc0 .Lprio_skip_0
	s_setprio 1

; template <class Epi, class Sched, bool ALIGN_EPI = false, bool SP2 = false>
; __device__ __forceinline__ void gemm_phase(PG8_LAS unsigned char* lds, const Gemm g, const Sched& S, const Epi& E, int wid_in) {
;     ...
;         const char* nA = has_next ? (const char*)g.A + (size_t)nxt.pm * tstep + (size_t)nxt.kt0 * kstep : cA; const char* nB = has_next ? (const char*)g.Bt + (size_t)nxt.pn * tstep + (size_t)nxt.kt0 * kstep : cB;
;         const int nt = cur.nkt;
;     ...
; #pragma unroll
;         for (int a = 0; a < 2; ++a)
; #pragma unroll
;             for (int b = 0; b < 2; ++b)
; #pragma unroll
;                 for (int m = 0; m < 4; ++m)
; #pragma unroll
;                     for (int n = 0; n < 2; ++n) acc[a][b][m][n] = (f32x4){0.f, 0.f, 0.f, 0.f};
.LBB0_847:
	s_ashr_i32 s19, s18, 31
	s_lshl_b64 s[22:23], s[18:19], 19
	s_add_u32 s17, s38, s22
	s_addc_u32 s19, s39, s23
	s_ashr_i32 s15, s14, 31
	s_lshl_b64 s[24:25], s[14:15], 7
	s_add_u32 s22, s17, s24
	s_addc_u32 s23, s19, s25
	s_and_b64 s[36:37], s[20:21], exec
	s_cselect_b32 s15, s23, s35
	s_cselect_b32 s19, s22, s34
	s_ashr_i32 s17, s16, 31
	s_lshl_b64 s[36:37], s[16:17], 19
	s_add_u32 s17, s52, s36
	s_addc_u32 s27, s53, s37
	s_add_u32 s24, s17, s24
	s_addc_u32 s25, s27, s25
	s_and_b64 s[36:37], s[20:21], exec
	s_cselect_b32 s17, s25, s31
	s_cselect_b32 s27, s24, s30
	s_add_i32 vcc_lo, s1, -2
	s_add_u32 vcc_hi, s30, 0x100
	s_addc_u32 s63, s31, 0
	s_add_u32 s30, s34, 0x40080
	v_mov_b32_e32 v2, 0
	s_addc_u32 s31, s35, 0
	s_mov_b32 s34, 0
	v_mov_b64_e32 v[2:3], 0
	v_mov_b64_e32 v[4:5], 0
	v_mov_b64_e32 v[6:7], 0
	v_mov_b64_e32 v[8:9], 0
	v_mov_b64_e32 v[10:11], 0
	v_mov_b64_e32 v[12:13], 0
	v_mov_b64_e32 v[14:15], 0
	v_mov_b64_e32 v[16:17], 0
	v_mov_b64_e32 v[18:19], 0
	v_mov_b64_e32 v[20:21], 0
	v_mov_b64_e32 v[22:23], 0
	v_mov_b64_e32 v[24:25], 0
	v_mov_b64_e32 v[26:27], 0
	v_mov_b64_e32 v[28:29], 0
	v_mov_b64_e32 v[30:31], 0
	v_mov_b64_e32 v[32:33], 0
	v_mov_b64_e32 v[34:35], 0
	v_mov_b64_e32 v[36:37], 0
	v_mov_b64_e32 v[38:39], 0
	v_mov_b64_e32 v[40:41], 0
	v_mov_b64_e32 v[42:43], 0
	v_mov_b64_e32 v[44:45], 0
	v_mov_b64_e32 v[46:47], 0
	v_mov_b64_e32 v[48:49], 0
	v_mov_b64_e32 v[50:51], 0
	v_mov_b64_e32 v[52:53], 0
	v_mov_b64_e32 v[54:55], 0
	v_mov_b64_e32 v[56:57], 0
	v_mov_b64_e32 v[58:59], 0
	v_mov_b64_e32 v[60:61], 0
	v_mov_b64_e32 v[62:63], 0
	v_mov_b64_e32 v[64:65], 0
	v_mov_b64_e32 v[66:67], 0
	v_mov_b64_e32 v[68:69], 0
	v_mov_b64_e32 v[70:71], 0
	v_mov_b64_e32 v[72:73], 0
	v_mov_b64_e32 v[74:75], 0
	v_mov_b64_e32 v[76:77], 0
	v_mov_b64_e32 v[78:79], 0
	v_mov_b64_e32 v[80:81], 0
	v_mov_b64_e32 v[82:83], 0
	v_mov_b64_e32 v[84:85], 0
	v_mov_b64_e32 v[86:87], 0
	v_mov_b64_e32 v[88:89], 0
	v_mov_b64_e32 v[90:91], 0
	v_mov_b64_e32 v[92:93], 0
	v_mov_b64_e32 v[94:95], 0
	v_mov_b64_e32 v[96:97], 0
	v_mov_b64_e32 v[98:99], 0
	v_mov_b64_e32 v[100:101], 0
	v_mov_b64_e32 v[102:103], 0
	v_mov_b64_e32 v[104:105], 0
	v_mov_b64_e32 v[106:107], 0
	v_mov_b64_e32 v[108:109], 0
	v_mov_b64_e32 v[110:111], 0
	v_mov_b64_e32 v[112:113], 0
	v_mov_b64_e32 v[114:115], 0
	v_mov_b64_e32 v[116:117], 0
	v_mov_b64_e32 v[118:119], 0
	v_mov_b64_e32 v[120:121], 0
	v_mov_b64_e32 v[122:123], 0
	v_mov_b64_e32 v[124:125], 0
	v_mov_b64_e32 v[126:127], 0
	v_mov_b64_e32 v[128:129], 0
	s_cmp_ge_u32 s47, 4
	s_cbranch_scc0 .Lprio_skip_1
	s_setprio 1

; template <class Epi, class Sched, bool ALIGN_EPI = false, bool SP2 = false>
; __device__ __forceinline__ void gemm_phase(PG8_LAS unsigned char* lds, const Gemm g, const Sched& S, const Epi& E, int wid_in) {
;     ...
;         const char* nA = has_next ? (const char*)g.A + (size_t)nxt.pm * tstep + (size_t)nxt.kt0 * kstep : cA; const char* nB = has_next ? (const char*)g.Bt + (size_t)nxt.pn * tstep + (size_t)nxt.kt0 * kstep : cB;
;         const int nt = cur.nkt;
;     ...
; #pragma unroll
;         for (int a = 0; a < 2; ++a)
; #pragma unroll
;             for (int b = 0; b < 2; ++b)
; #pragma unroll
;                 for (int m = 0; m < 4; ++m)
; #pragma unroll
;                     for (int n = 0; n < 2; ++n) acc[a][b][m][n] = (f32x4){0.f, 0.f, 0.f, 0.f};
.LBB0_1020:
	s_add_i32 s17, s90, -2
	s_add_u32 s19, s30, 0x100
	s_addc_u32 s21, s31, 0
	s_add_u32 s30, s34, 0x80080
	v_mov_b32_e32 v2, 0
	s_addc_u32 s31, s35, 0
	s_mov_b32 s27, 0
	v_mov_b64_e32 v[2:3], 0
	v_mov_b64_e32 v[4:5], 0
	v_mov_b64_e32 v[6:7], 0
	v_mov_b64_e32 v[8:9], 0
	v_mov_b64_e32 v[10:11], 0
	v_mov_b64_e32 v[12:13], 0
	v_mov_b64_e32 v[14:15], 0
	v_mov_b64_e32 v[16:17], 0
	v_mov_b64_e32 v[18:19], 0
	v_mov_b64_e32 v[20:21], 0
	v_mov_b64_e32 v[22:23], 0
	v_mov_b64_e32 v[24:25], 0
	v_mov_b64_e32 v[26:27], 0
	v_mov_b64_e32 v[28:29], 0
	v_mov_b64_e32 v[30:31], 0
	v_mov_b64_e32 v[32:33], 0
	v_mov_b64_e32 v[34:35], 0
	v_mov_b64_e32 v[36:37], 0
	v_mov_b64_e32 v[38:39], 0
	v_mov_b64_e32 v[40:41], 0
	v_mov_b64_e32 v[42:43], 0
	v_mov_b64_e32 v[44:45], 0
	v_mov_b64_e32 v[46:47], 0
	v_mov_b64_e32 v[48:49], 0
	v_mov_b64_e32 v[50:51], 0
	v_mov_b64_e32 v[52:53], 0
	v_mov_b64_e32 v[54:55], 0
	v_mov_b64_e32 v[56:57], 0
	v_mov_b64_e32 v[58:59], 0
	v_mov_b64_e32 v[60:61], 0
	v_mov_b64_e32 v[62:63], 0
	v_mov_b64_e32 v[64:65], 0
	v_mov_b64_e32 v[66:67], 0
	v_mov_b64_e32 v[68:69], 0
	v_mov_b64_e32 v[70:71], 0
	v_mov_b64_e32 v[72:73], 0
	v_mov_b64_e32 v[74:75], 0
	v_mov_b64_e32 v[76:77], 0
	v_mov_b64_e32 v[78:79], 0
	v_mov_b64_e32 v[80:81], 0
	v_mov_b64_e32 v[82:83], 0
	v_mov_b64_e32 v[84:85], 0
	v_mov_b64_e32 v[86:87], 0
	v_mov_b64_e32 v[88:89], 0
	v_mov_b64_e32 v[90:91], 0
	v_mov_b64_e32 v[92:93], 0
	v_mov_b64_e32 v[94:95], 0
	v_mov_b64_e32 v[96:97], 0
	v_mov_b64_e32 v[98:99], 0
	v_mov_b64_e32 v[100:101], 0
	v_mov_b64_e32 v[102:103], 0
	v_mov_b64_e32 v[104:105], 0
	v_mov_b64_e32 v[106:107], 0
	v_mov_b64_e32 v[108:109], 0
	v_mov_b64_e32 v[110:111], 0
	v_mov_b64_e32 v[112:113], 0
	v_mov_b64_e32 v[114:115], 0
	v_mov_b64_e32 v[116:117], 0
	v_mov_b64_e32 v[118:119], 0
	v_mov_b64_e32 v[120:121], 0
	v_mov_b64_e32 v[122:123], 0
	v_mov_b64_e32 v[124:125], 0
	v_mov_b64_e32 v[126:127], 0
	v_mov_b64_e32 v[128:129], 0
	s_cmp_ge_u32 s47, 4
	s_cbranch_scc0 .Lprio_skip_3
	s_setprio 1

; template <class Epi, class Sched, bool ALIGN_EPI = false, bool SP2 = false>
; __device__ __forceinline__ void gemm_phase(PG8_LAS unsigned char* lds, const Gemm g, const Sched& S, const Epi& E, int wid_in) {
;     ...
;         const char* nA = has_next ? (const char*)g.A + (size_t)nxt.pm * tstep + (size_t)nxt.kt0 * kstep : cA; const char* nB = has_next ? (const char*)g.Bt + (size_t)nxt.pn * tstep + (size_t)nxt.kt0 * kstep : cB;
;         const int nt = cur.nkt;
;     ...
; #pragma unroll
;         for (int a = 0; a < 2; ++a)
; #pragma unroll
;             for (int b = 0; b < 2; ++b)
; #pragma unroll
;                 for (int m = 0; m < 4; ++m)
; #pragma unroll
;                     for (int n = 0; n < 2; ++n) acc[a][b][m][n] = (f32x4){0.f, 0.f, 0.f, 0.f};
.LBB0_1152:
	s_ashr_i32 s19, s18, 31
	s_lshl_b64 s[20:21], s[18:19], 20
	s_add_u32 s20, s0, s20
	s_addc_u32 s21, s1, s21
	s_and_b64 s[22:23], s[8:9], exec
	s_cselect_b32 s19, s21, s25
	s_cselect_b32 s64, s20, s24
	s_ashr_i32 s17, s16, 31
	s_lshl_b64 s[22:23], s[16:17], 20
	s_add_u32 s22, s30, s22
	s_addc_u32 s23, s31, s23
	s_and_b64 s[28:29], s[8:9], exec
	s_cselect_b32 s17, s23, s27
	s_cselect_b32 s65, s22, s26
	s_add_u32 s72, s26, 0x100
	s_addc_u32 s63, s27, 0
	s_add_u32 s24, s24, 0x80080
	v_mov_b32_e32 v2, 0
	s_addc_u32 s25, s25, 0
	s_mov_b32 s73, -2
	v_mov_b64_e32 v[2:3], 0
	v_mov_b64_e32 v[4:5], 0
	v_mov_b64_e32 v[6:7], 0
	v_mov_b64_e32 v[8:9], 0
	v_mov_b64_e32 v[10:11], 0
	v_mov_b64_e32 v[12:13], 0
	v_mov_b64_e32 v[14:15], 0
	v_mov_b64_e32 v[16:17], 0
	v_mov_b64_e32 v[18:19], 0
	v_mov_b64_e32 v[20:21], 0
	v_mov_b64_e32 v[22:23], 0
	v_mov_b64_e32 v[24:25], 0
	v_mov_b64_e32 v[26:27], 0
	v_mov_b64_e32 v[28:29], 0
	v_mov_b64_e32 v[30:31], 0
	v_mov_b64_e32 v[32:33], 0
	v_mov_b64_e32 v[34:35], 0
	v_mov_b64_e32 v[36:37], 0
	v_mov_b64_e32 v[38:39], 0
	v_mov_b64_e32 v[40:41], 0
	v_mov_b64_e32 v[42:43], 0
	v_mov_b64_e32 v[44:45], 0
	v_mov_b64_e32 v[46:47], 0
	v_mov_b64_e32 v[48:49], 0
	v_mov_b64_e32 v[50:51], 0
	v_mov_b64_e32 v[52:53], 0
	v_mov_b64_e32 v[54:55], 0
	v_mov_b64_e32 v[56:57], 0
	v_mov_b64_e32 v[58:59], 0
	v_mov_b64_e32 v[60:61], 0
	v_mov_b64_e32 v[62:63], 0
	v_mov_b64_e32 v[64:65], 0
	v_mov_b64_e32 v[66:67], 0
	v_mov_b64_e32 v[68:69], 0
	v_mov_b64_e32 v[70:71], 0
	v_mov_b64_e32 v[72:73], 0
	v_mov_b64_e32 v[74:75], 0
	v_mov_b64_e32 v[76:77], 0
	v_mov_b64_e32 v[78:79], 0
	v_mov_b64_e32 v[80:81], 0
	v_mov_b64_e32 v[82:83], 0
	v_mov_b64_e32 v[84:85], 0
	v_mov_b64_e32 v[86:87], 0
	v_mov_b64_e32 v[88:89], 0
	v_mov_b64_e32 v[90:91], 0
	v_mov_b64_e32 v[92:93], 0
	v_mov_b64_e32 v[94:95], 0
	v_mov_b64_e32 v[96:97], 0
	v_mov_b64_e32 v[98:99], 0
	v_mov_b64_e32 v[100:101], 0
	v_mov_b64_e32 v[102:103], 0
	v_mov_b64_e32 v[104:105], 0
	v_mov_b64_e32 v[106:107], 0
	v_mov_b64_e32 v[108:109], 0
	v_mov_b64_e32 v[110:111], 0
	v_mov_b64_e32 v[112:113], 0
	v_mov_b64_e32 v[114:115], 0
	v_mov_b64_e32 v[116:117], 0
	v_mov_b64_e32 v[118:119], 0
	v_mov_b64_e32 v[120:121], 0
	v_mov_b64_e32 v[122:123], 0
	v_mov_b64_e32 v[124:125], 0
	v_mov_b64_e32 v[126:127], 0
	v_mov_b64_e32 v[128:129], 0
	s_cmp_ge_u32 s47, 4
	s_cbranch_scc0 .Lprio_skip_4
	s_setprio 1

; template <class Epi, class Sched, bool ALIGN_EPI = false, bool SP2 = false>
; __device__ __forceinline__ void gemm_phase(PG8_LAS unsigned char* lds, const Gemm g, const Sched& S, const Epi& E, int wid_in) {
;     ...
;         const char* nA = has_next ? (const char*)g.A + (size_t)nxt.pm * tstep + (size_t)nxt.kt0 * kstep : cA; const char* nB = has_next ? (const char*)g.Bt + (size_t)nxt.pn * tstep + (size_t)nxt.kt0 * kstep : cB;
;         const int nt = cur.nkt;
;     ...
; #pragma unroll
;         for (int a = 0; a < 2; ++a)
; #pragma unroll
;             for (int b = 0; b < 2; ++b)
; #pragma unroll
;                 for (int m = 0; m < 4; ++m)
; #pragma unroll
;                     for (int n = 0; n < 2; ++n) acc[a][b][m][n] = (f32x4){0.f, 0.f, 0.f, 0.f};
.LBB0_1232:
	s_add_i32 s17, s90, -2
	s_add_u32 s19, s30, 0x100
	s_addc_u32 s21, s31, 0
	s_add_u32 s30, s34, 0x200080
	v_mov_b32_e32 v2, 0
	s_addc_u32 s31, s35, 0
	s_mov_b32 s27, 0
	v_mov_b64_e32 v[2:3], 0
	v_mov_b64_e32 v[4:5], 0
	v_mov_b64_e32 v[6:7], 0
	v_mov_b64_e32 v[8:9], 0
	v_mov_b64_e32 v[10:11], 0
	v_mov_b64_e32 v[12:13], 0
	v_mov_b64_e32 v[14:15], 0
	v_mov_b64_e32 v[16:17], 0
	v_mov_b64_e32 v[18:19], 0
	v_mov_b64_e32 v[20:21], 0
	v_mov_b64_e32 v[22:23], 0
	v_mov_b64_e32 v[24:25], 0
	v_mov_b64_e32 v[26:27], 0
	v_mov_b64_e32 v[28:29], 0
	v_mov_b64_e32 v[30:31], 0
	v_mov_b64_e32 v[32:33], 0
	v_mov_b64_e32 v[34:35], 0
	v_mov_b64_e32 v[36:37], 0
	v_mov_b64_e32 v[38:39], 0
	v_mov_b64_e32 v[40:41], 0
	v_mov_b64_e32 v[42:43], 0
	v_mov_b64_e32 v[44:45], 0
	v_mov_b64_e32 v[46:47], 0
	v_mov_b64_e32 v[48:49], 0
	v_mov_b64_e32 v[50:51], 0
	v_mov_b64_e32 v[52:53], 0
	v_mov_b64_e32 v[54:55], 0
	v_mov_b64_e32 v[56:57], 0
	v_mov_b64_e32 v[58:59], 0
	v_mov_b64_e32 v[60:61], 0
	v_mov_b64_e32 v[62:63], 0
	v_mov_b64_e32 v[64:65], 0
	v_mov_b64_e32 v[66:67], 0
	v_mov_b64_e32 v[68:69], 0
	v_mov_b64_e32 v[70:71], 0
	v_mov_b64_e32 v[72:73], 0
	v_mov_b64_e32 v[74:75], 0
	v_mov_b64_e32 v[76:77], 0
	v_mov_b64_e32 v[78:79], 0
	v_mov_b64_e32 v[80:81], 0
	v_mov_b64_e32 v[82:83], 0
	v_mov_b64_e32 v[84:85], 0
	v_mov_b64_e32 v[86:87], 0
	v_mov_b64_e32 v[88:89], 0
	v_mov_b64_e32 v[90:91], 0
	v_mov_b64_e32 v[92:93], 0
	v_mov_b64_e32 v[94:95], 0
	v_mov_b64_e32 v[96:97], 0
	v_mov_b64_e32 v[98:99], 0
	v_mov_b64_e32 v[100:101], 0
	v_mov_b64_e32 v[102:103], 0
	v_mov_b64_e32 v[104:105], 0
	v_mov_b64_e32 v[106:107], 0
	v_mov_b64_e32 v[108:109], 0
	v_mov_b64_e32 v[110:111], 0
	v_mov_b64_e32 v[112:113], 0
	v_mov_b64_e32 v[114:115], 0
	v_mov_b64_e32 v[116:117], 0
	v_mov_b64_e32 v[118:119], 0
	v_mov_b64_e32 v[120:121], 0
	v_mov_b64_e32 v[122:123], 0
	v_mov_b64_e32 v[124:125], 0
	v_mov_b64_e32 v[126:127], 0
	v_mov_b64_e32 v[128:129], 0
	s_cmp_ge_u32 s47, 4
	s_cbranch_scc0 .Lprio_skip_5
	s_setprio 1
